# on top of the packed-multiply split: HGRN pass-3 prologue gate loads batched into one wait, and cross-attention tile K/V loads (now global loads) issued ahead of the top-of-tile barrier
# baseline (speedup 1.0000x reference)
; template <int DQK, int DV, int NDP, int MODE, bool PF>
; DEV void attn_unit(unsigned char* lds, const bf16_t* Q, int ldq, const bf16_t* K, int ldk, const bf16_t* VT, int ldvt, bf16_t* O, int ldo,
;                    int kt0, int ntiles, int qpos0, const float* biasg, float sinkl2) {
;     ...
;         __syncthreads();
;         if (!PF) ATT_GLOAD(kt);
;         ATT_LSTORE();
;         if (MODE == 1 && ti == 0) { for (int i = tid; i < 257; i += 512) bt[i] = biasg[i]; }
;         __syncthreads();
;         if (PF && ti + 1 < ntiles) ATT_GLOAD(kt + 64);
.LBB0_1709:
	v_lshl_add_u64 v[64:65], s[8:9], 0, v[178:179]
	v_lshl_add_u64 v[68:69], s[8:9], 0, v[176:177]
	v_lshl_add_u64 v[72:73], s[8:9], 0, v[174:175]
	v_lshl_add_u64 v[76:77], s[8:9], 0, v[172:173]
	v_lshl_add_u64 v[80:81], s[8:9], 0, v[170:171]
	v_lshl_add_u64 v[84:85], s[8:9], 0, v[168:169]
	v_lshl_add_u64 v[88:89], s[8:9], 0, v[166:167]
	v_lshl_add_u64 v[92:93], s[8:9], 0, v[164:165]
	global_load_dwordx4 v[64:67], v[64:65], off
	s_nop 0
	global_load_dwordx4 v[68:71], v[68:69], off
	s_nop 0
	global_load_dwordx4 v[72:75], v[72:73], off
	s_nop 0
	global_load_dwordx4 v[76:79], v[76:77], off
	s_nop 0
	global_load_dwordx4 v[80:83], v[80:81], off
	s_nop 0
	global_load_dwordx4 v[84:87], v[84:85], off
	s_nop 0
	global_load_dwordx4 v[88:91], v[88:89], off
	s_nop 0
	global_load_dwordx4 v[92:95], v[92:93], off
	s_waitcnt lgkmcnt(0)
	s_barrier
	s_add_i32 s20, s20, -1
	v_lshl_add_u64 v[164:165], v[164:165], 0, s[82:83]
	v_lshl_add_u64 v[166:167], v[166:167], 0, s[82:83]
	v_lshl_add_u64 v[168:169], v[168:169], 0, s[82:83]
	v_lshl_add_u64 v[170:171], v[170:171], 0, s[82:83]
	v_lshl_add_u64 v[172:173], v[172:173], 0, s[78:79]
	v_lshl_add_u64 v[174:175], v[174:175], 0, s[78:79]
	v_lshl_add_u64 v[176:177], v[176:177], 0, s[78:79]
	v_lshl_add_u64 v[178:179], v[178:179], 0, s[78:79]
	s_cmp_lg_u32 s20, 0
	s_waitcnt vmcnt(0) lgkmcnt(0)
	ds_write_b128 v192, v[64:67]
	ds_write_b128 v193, v[68:71]
	ds_write_b128 v194, v[72:75]
	ds_write_b128 v195, v[76:79]
	ds_write_b128 v196, v[80:83] offset:33792
	ds_write_b128 v197, v[84:87] offset:33792
	ds_write_b128 v198, v[88:91] offset:33792
	ds_write_b128 v199, v[92:95] offset:33792
	s_waitcnt lgkmcnt(0)
	s_barrier
	ds_read_b128 v[64:67], v191
	ds_read_b128 v[180:183], v191 offset:32
	s_waitcnt lgkmcnt(1)
	v_mfma_f32_32x32x16_bf16 v[64:79], v[64:67], v[96:99], 0
	ds_read_b128 v[80:83], v191 offset:16896
	ds_read_b128 v[184:187], v191 offset:16928
	s_waitcnt lgkmcnt(1)
	v_mfma_f32_32x32x16_bf16 v[80:95], v[80:83], v[96:99], 0
	v_mfma_f32_32x32x16_bf16 v[64:79], v[180:183], v[100:103], v[64:79]
	s_waitcnt lgkmcnt(0)
	v_mfma_f32_32x32x16_bf16 v[80:95], v[184:187], v[100:103], v[80:95]
	ds_read_b128 v[180:183], v191 offset:64
	ds_read_b128 v[184:187], v191 offset:96
	s_waitcnt lgkmcnt(1)
	v_mfma_f32_32x32x16_bf16 v[64:79], v[180:183], v[104:107], v[64:79]
	ds_read_b128 v[180:183], v191 offset:16960
	ds_read_b128 v[200:203], v191 offset:16992
	s_waitcnt lgkmcnt(1)
	v_mfma_f32_32x32x16_bf16 v[80:95], v[180:183], v[104:107], v[80:95]
	v_mfma_f32_32x32x16_bf16 v[64:79], v[184:187], v[108:111], v[64:79]
	ds_read_b128 v[180:183], v191 offset:128
	ds_read_b128 v[184:187], v191 offset:160
	s_waitcnt lgkmcnt(2)
	v_mfma_f32_32x32x16_bf16 v[80:95], v[200:203], v[108:111], v[80:95]
	s_waitcnt lgkmcnt(1)
	v_mfma_f32_32x32x16_bf16 v[64:79], v[180:183], v[112:115], v[64:79]
	ds_read_b128 v[180:183], v191 offset:17024
	ds_read_b128 v[200:203], v191 offset:17056
	s_waitcnt lgkmcnt(1)
	v_mfma_f32_32x32x16_bf16 v[80:95], v[180:183], v[112:115], v[80:95]
	v_mfma_f32_32x32x16_bf16 v[64:79], v[184:187], v[116:119], v[64:79]
	ds_read_b128 v[180:183], v191 offset:192
	ds_read_b128 v[184:187], v191 offset:224
	s_waitcnt lgkmcnt(2)
	v_mfma_f32_32x32x16_bf16 v[80:95], v[200:203], v[116:119], v[80:95]
	s_waitcnt lgkmcnt(1)
	v_mfma_f32_32x32x16_bf16 v[64:79], v[180:183], v[120:123], v[64:79]
	ds_read_b128 v[180:183], v191 offset:17088
	ds_read_b128 v[200:203], v191 offset:17120
	s_waitcnt lgkmcnt(1)
	v_mfma_f32_32x32x16_bf16 v[80:95], v[180:183], v[120:123], v[80:95]
	v_mfma_f32_32x32x16_bf16 v[64:79], v[184:187], v[124:127], v[64:79]
	ds_read_b128 v[180:183], v191 offset:256
	ds_read_b128 v[184:187], v191 offset:288
	s_waitcnt lgkmcnt(2)
	v_mfma_f32_32x32x16_bf16 v[80:95], v[200:203], v[124:127], v[80:95]
	s_waitcnt lgkmcnt(1)
	v_mfma_f32_32x32x16_bf16 v[64:79], v[180:183], v[130:133], v[64:79]
	ds_read_b128 v[180:183], v191 offset:17152
	ds_read_b128 v[200:203], v191 offset:17184
	s_waitcnt lgkmcnt(1)
	v_mfma_f32_32x32x16_bf16 v[80:95], v[180:183], v[130:133], v[80:95]
	v_mfma_f32_32x32x16_bf16 v[64:79], v[184:187], v[134:137], v[64:79]
	ds_read_b128 v[180:183], v191 offset:320
	ds_read_b128 v[184:187], v191 offset:352
	s_waitcnt lgkmcnt(2)
	v_mfma_f32_32x32x16_bf16 v[80:95], v[200:203], v[134:137], v[80:95]
	s_waitcnt lgkmcnt(1)
	v_mfma_f32_32x32x16_bf16 v[64:79], v[180:183], v[138:141], v[64:79]
	ds_read_b128 v[180:183], v191 offset:17216
	ds_read_b128 v[200:203], v191 offset:17248
	s_waitcnt lgkmcnt(1)
	v_mfma_f32_32x32x16_bf16 v[80:95], v[180:183], v[138:141], v[80:95]
	v_mfma_f32_32x32x16_bf16 v[64:79], v[184:187], v[142:145], v[64:79]
	ds_read_b128 v[180:183], v191 offset:384
	ds_read_b128 v[184:187], v191 offset:416
	s_waitcnt lgkmcnt(2)
	v_mfma_f32_32x32x16_bf16 v[80:95], v[200:203], v[142:145], v[80:95]
	s_waitcnt lgkmcnt(1)
	v_mfma_f32_32x32x16_bf16 v[64:79], v[180:183], v[146:149], v[64:79]
	ds_read_b128 v[180:183], v191 offset:17280
	ds_read_b128 v[200:203], v191 offset:17312
	s_waitcnt lgkmcnt(1)
	v_mfma_f32_32x32x16_bf16 v[80:95], v[180:183], v[146:149], v[80:95]
	v_mfma_f32_32x32x16_bf16 v[64:79], v[184:187], v[150:153], v[64:79]
	ds_read_b128 v[180:183], v191 offset:448
	ds_read_b128 v[184:187], v191 offset:480
	s_waitcnt lgkmcnt(2)
	v_mfma_f32_32x32x16_bf16 v[80:95], v[200:203], v[150:153], v[80:95]
	s_waitcnt lgkmcnt(1)
	v_mfma_f32_32x32x16_bf16 v[64:79], v[180:183], v[154:157], v[64:79]
	ds_read_b128 v[180:183], v191 offset:17344
	ds_read_b128 v[200:203], v191 offset:17376
	s_waitcnt lgkmcnt(1)
	v_mfma_f32_32x32x16_bf16 v[80:95], v[180:183], v[154:157], v[80:95]
	v_mfma_f32_32x32x16_bf16 v[64:79], v[184:187], v[158:161], v[64:79]
	s_waitcnt lgkmcnt(0)
; DEV unsigned pk2(float lo, float hi) { return pg8::cvt_pk_bf16(lo, hi); }
; template <int DQK, int DV, int NDP, int MODE, bool PF>
; DEV void attn_unit(unsigned char* lds, const bf16_t* Q, int ldq, const bf16_t* K, int ldk, const bf16_t* VT, int ldvt, bf16_t* O, int ldo,
;                    int kt0, int ntiles, int qpos0, const float* biasg, float sinkl2) {
;     ...
;             float mx = fmaxf(p0[0], p1[0]);
; #pragma unroll
;             for (int r = 1; r < 16; ++r) mx = fmaxf(mx, fmaxf(p0[r], p1[r]));
;             mx = fmaxf(mx, __shfl_xor(mx, 32));
;             const float mnew = fmaxf(mrun, mx), alpha = __builtin_amdgcn_exp2f(mrun - mnew); mrun = mnew;
;             float rsum = 0.f;
; #pragma unroll
;             for (int r = 0; r < 16; ++r) { p0[r] = __builtin_amdgcn_exp2f(p0[r] - mnew); p1[r] = __builtin_amdgcn_exp2f(p1[r] - mnew); rsum += p0[r] + p1[r]; }
;             lrun = lrun * alpha + rsum;
; #pragma unroll
;             for (int i = 0; i < NDB; ++i)
; #pragma unroll
;                 for (int r = 0; r < 16; ++r) o[i][r] *= alpha;
;             bf16x8 pb[4];
; #pragma unroll
;             for (int ks = 0; ks < 4; ++ks) { u32x4 w;
;                 if (ks < 2) { w.x = pk2(p0[8 * ks + 0], p0[8 * ks + 1]); w.y = pk2(p0[8 * ks + 2], p0[8 * ks + 3]); w.z = pk2(p0[8 * ks + 4], p0[8 * ks + 5]); w.w = pk2(p0[8 * ks + 6], p0[8 * ks + 7]); }
;                 else { const int k2 = ks - 2; w.x = pk2(p1[8 * k2 + 0], p1[8 * k2 + 1]); w.y = pk2(p1[8 * k2 + 2], p1[8 * k2 + 3]); w.z = pk2(p1[8 * k2 + 4], p1[8 * k2 + 5]); w.w = pk2(p1[8 * k2 + 6], p1[8 * k2 + 7]); }
;                 pb[ks] = __builtin_bit_cast(bf16x8, w); }
; #pragma unroll
;             for (int db = 0; db < NDB; ++db)
; #pragma unroll
;                 for (int ks = 0; ks < 4; ++ks) {
;                     const bf16x8 vf = *(const bf16x8*)(Vt + (dp * DVW + db * 32 + r32) * VP + ks * 16 + hi * 8);
;                     o[db] = __builtin_amdgcn_mfma_f32_32x32x16_bf16(vf, pb[ks], o[db], 0, 0, 0);
	v_mfma_f32_32x32x16_bf16 v[80:95], v[200:203], v[158:161], v[80:95]
	s_nop 9
	v_max_f32_e32 v181, v65, v65
	v_max_f32_e32 v183, v66, v66
	v_max_f32_e32 v185, v67, v67
	v_max_f32_e32 v187, v68, v68
	v_max_f32_e32 v189, v69, v69
	v_max_f32_e32 v201, v70, v70
	v_max_f32_e32 v203, v71, v71
	v_max_f32_e32 v180, v81, v81
	v_max_f32_e32 v182, v82, v82
	v_max_f32_e32 v184, v83, v83
	v_max_f32_e32 v180, v181, v180
	v_max_f32_e32 v186, v84, v84
	v_max_f32_e32 v188, v85, v85
	v_max_f32_e32 v181, v183, v182
	v_max_f32_e32 v182, v185, v184
	v_max3_f32 v180, v64, v80, v180
	v_max_f32_e32 v200, v86, v86
	v_max_f32_e32 v202, v87, v87
	v_max_f32_e32 v183, v187, v186
	v_max_f32_e32 v184, v189, v188
	v_max3_f32 v180, v180, v181, v182
	v_max_f32_e32 v204, v88, v88
	v_max_f32_e32 v205, v72, v72
	v_max_f32_e32 v207, v89, v89
	v_max_f32_e32 v208, v73, v73
	v_max_f32_e32 v185, v201, v200
	v_max_f32_e32 v186, v203, v202
	v_max3_f32 v180, v180, v183, v184
	v_max_f32_e32 v209, v90, v90
	v_max_f32_e32 v210, v74, v74
	v_max_f32_e32 v211, v91, v91
	v_max_f32_e32 v212, v75, v75
	v_max_f32_e32 v187, v205, v204
	v_max_f32_e32 v188, v208, v207
	v_max3_f32 v180, v180, v185, v186
	v_max_f32_e32 v213, v92, v92
	v_max_f32_e32 v214, v76, v76
	v_max_f32_e32 v215, v93, v93
	v_max_f32_e32 v218, v77, v77
	v_max_f32_e32 v189, v210, v209
	v_max_f32_e32 v200, v212, v211
	v_max3_f32 v180, v180, v187, v188
	v_max_f32_e32 v219, v94, v94
	v_max_f32_e32 v220, v78, v78
	v_max_f32_e32 v221, v95, v95
	v_max_f32_e32 v222, v79, v79
	v_max_f32_e32 v201, v214, v213
	v_max_f32_e32 v202, v218, v215
	v_max3_f32 v180, v180, v189, v200
	v_max_f32_e32 v203, v220, v219
	v_max_f32_e32 v204, v222, v221
	v_max3_f32 v180, v180, v201, v202
	v_max3_f32 v180, v180, v203, v204
	ds_bpermute_b32 v181, v190, v180
	v_mov_b32_e32 v215, v216
	s_waitcnt lgkmcnt(0)
	v_max3_f32 v207, v217, v180, v181
	v_sub_f32_e32 v180, v217, v207
	v_sub_f32_e32 v64, v64, v207
	v_sub_f32_e32 v181, v80, v207
	v_sub_f32_e32 v65, v65, v207
	v_sub_f32_e32 v182, v81, v207
	v_sub_f32_e32 v66, v66, v207
	v_sub_f32_e32 v82, v82, v207
	v_sub_f32_e32 v67, v67, v207
	v_sub_f32_e32 v83, v83, v207
	v_sub_f32_e32 v68, v68, v207
	v_sub_f32_e32 v84, v84, v207
	v_sub_f32_e32 v69, v69, v207
	v_sub_f32_e32 v183, v85, v207
	v_sub_f32_e32 v70, v70, v207
	v_sub_f32_e32 v86, v86, v207
	v_sub_f32_e32 v71, v71, v207
	v_sub_f32_e32 v184, v87, v207
	v_sub_f32_e32 v72, v72, v207
	v_sub_f32_e32 v185, v88, v207
	v_sub_f32_e32 v73, v73, v207
	v_sub_f32_e32 v186, v89, v207
	v_sub_f32_e32 v74, v74, v207
	v_sub_f32_e32 v187, v90, v207
	v_sub_f32_e32 v75, v75, v207
	v_sub_f32_e32 v188, v91, v207
	v_sub_f32_e32 v76, v76, v207
	v_sub_f32_e32 v189, v92, v207
	v_sub_f32_e32 v77, v77, v207
	v_sub_f32_e32 v200, v93, v207
	v_sub_f32_e32 v78, v78, v207
	v_sub_f32_e32 v201, v94, v207
	v_sub_f32_e32 v79, v79, v207
	v_sub_f32_e32 v202, v95, v207
	v_exp_f32_e32 v80, v180
	v_exp_f32_e32 v81, v64
	v_exp_f32_e32 v209, v181
	v_exp_f32_e32 v208, v65
	v_exp_f32_e32 v211, v182
	v_exp_f32_e32 v210, v66
	v_exp_f32_e32 v213, v82
	v_exp_f32_e32 v212, v67
	v_exp_f32_e32 v214, v83
	v_exp_f32_e32 v83, v68
	v_exp_f32_e32 v85, v84
	v_exp_f32_e32 v82, v69
	v_exp_f32_e32 v84, v183
	v_exp_f32_e32 v87, v70
	v_exp_f32_e32 v89, v86
	v_exp_f32_e32 v86, v71
	v_exp_f32_e32 v88, v184
	v_exp_f32_e32 v91, v72
	v_exp_f32_e32 v93, v185
	v_exp_f32_e32 v90, v73
	v_exp_f32_e32 v92, v186
	v_exp_f32_e32 v95, v74
	v_exp_f32_e32 v181, v187
	v_exp_f32_e32 v94, v75
	v_exp_f32_e32 v180, v188
	v_exp_f32_e32 v183, v76
	v_exp_f32_e32 v185, v189
	v_exp_f32_e32 v182, v77
	v_exp_f32_e32 v184, v200
	v_exp_f32_e32 v187, v78
	v_exp_f32_e32 v189, v201
	v_exp_f32_e32 v186, v79
	v_exp_f32_e32 v188, v202
	v_cvt_pk_bf16_f32 v200, v81, v208
	v_cvt_pk_bf16_f32 v201, v210, v212
	v_cvt_pk_bf16_f32 v202, v83, v82
	v_cvt_pk_bf16_f32 v203, v87, v86
	v_cvt_pk_bf16_f32 v72, v91, v90
	v_cvt_pk_bf16_f32 v73, v95, v94
	v_cvt_pk_bf16_f32 v74, v183, v182
	v_cvt_pk_bf16_f32 v75, v187, v186
	v_cvt_pk_bf16_f32 v68, v209, v211
	v_cvt_pk_bf16_f32 v69, v213, v214
	v_cvt_pk_bf16_f32 v70, v85, v84
	v_cvt_pk_bf16_f32 v71, v89, v88
	v_cvt_pk_bf16_f32 v64, v93, v92
	v_cvt_pk_bf16_f32 v65, v181, v180
	v_cvt_pk_bf16_f32 v66, v185, v184
	v_cvt_pk_bf16_f32 v67, v189, v188
	ds_read_b128 v[76:79], v206 offset:33792
	ds_read_b128 v[218:221], v206 offset:33824
	ds_read_b128 v[230:233], v206 offset:38400
	v_pk_mul_f32 v[62:63], v[62:63], v[80:81] op_sel_hi:[1,0]
	v_pk_mul_f32 v[60:61], v[60:61], v[80:81] op_sel_hi:[1,0]
	v_pk_mul_f32 v[58:59], v[58:59], v[80:81] op_sel_hi:[1,0]
	v_pk_mul_f32 v[56:57], v[56:57], v[80:81] op_sel_hi:[1,0]
	v_pk_mul_f32 v[54:55], v[54:55], v[80:81] op_sel_hi:[1,0]
	v_pk_mul_f32 v[52:53], v[52:53], v[80:81] op_sel_hi:[1,0]
	v_pk_mul_f32 v[50:51], v[50:51], v[80:81] op_sel_hi:[1,0]
	v_pk_mul_f32 v[48:49], v[48:49], v[80:81] op_sel_hi:[1,0]
	v_pk_mul_f32 v[46:47], v[46:47], v[80:81] op_sel_hi:[1,0]
	v_pk_mul_f32 v[44:45], v[44:45], v[80:81] op_sel_hi:[1,0]
	v_pk_mul_f32 v[42:43], v[42:43], v[80:81] op_sel_hi:[1,0]
	v_pk_mul_f32 v[40:41], v[40:41], v[80:81] op_sel_hi:[1,0]
	v_pk_mul_f32 v[38:39], v[38:39], v[80:81] op_sel_hi:[1,0]
	v_pk_mul_f32 v[36:37], v[36:37], v[80:81] op_sel_hi:[1,0]
	v_pk_mul_f32 v[34:35], v[34:35], v[80:81] op_sel_hi:[1,0]
	v_pk_mul_f32 v[32:33], v[32:33], v[80:81] op_sel_hi:[1,0]
	s_waitcnt lgkmcnt(2)
	v_mfma_f32_32x32x16_bf16 v[48:63], v[76:79], v[200:203], v[48:63]
	ds_read_b128 v[234:237], v206 offset:38432
	ds_read_b128 v[76:79], v206 offset:43008
	v_mul_f32_e64 v30, v30, v80
	v_mul_f32_e64 v31, v31, v80
	v_mul_f32_e64 v28, v28, v80
	v_mul_f32_e64 v29, v29, v80
	v_pk_mul_f32 v[26:27], v[26:27], v[80:81] op_sel_hi:[1,0]
	v_pk_mul_f32 v[24:25], v[24:25], v[80:81] op_sel_hi:[1,0]
	v_pk_mul_f32 v[22:23], v[22:23], v[80:81] op_sel_hi:[1,0]
	v_pk_mul_f32 v[20:21], v[20:21], v[80:81] op_sel_hi:[1,0]
	s_waitcnt lgkmcnt(2)
; DEV unsigned pk2(float lo, float hi) { return pg8::cvt_pk_bf16(lo, hi); }
; template <int DQK, int DV, int NDP, int MODE, bool PF>
; DEV void attn_unit(unsigned char* lds, const bf16_t* Q, int ldq, const bf16_t* K, int ldk, const bf16_t* VT, int ldvt, bf16_t* O, int ldo,
;                    int kt0, int ntiles, int qpos0, const float* biasg, float sinkl2) {
;     ...
;             for (int r = 0; r < 16; ++r) { p0[r] = __builtin_amdgcn_exp2f(p0[r] - mnew); p1[r] = __builtin_amdgcn_exp2f(p1[r] - mnew); rsum += p0[r] + p1[r]; }
;             lrun = lrun * alpha + rsum;
; #pragma unroll
;             for (int i = 0; i < NDB; ++i)
; #pragma unroll
;                 for (int r = 0; r < 16; ++r) o[i][r] *= alpha;
;             bf16x8 pb[4];
; #pragma unroll
;             for (int ks = 0; ks < 4; ++ks) { u32x4 w;
;                 if (ks < 2) { w.x = pk2(p0[8 * ks + 0], p0[8 * ks + 1]); w.y = pk2(p0[8 * ks + 2], p0[8 * ks + 3]); w.z = pk2(p0[8 * ks + 4], p0[8 * ks + 5]); w.w = pk2(p0[8 * ks + 6], p0[8 * ks + 7]); }
;                 else { const int k2 = ks - 2; w.x = pk2(p1[8 * k2 + 0], p1[8 * k2 + 1]); w.y = pk2(p1[8 * k2 + 2], p1[8 * k2 + 3]); w.z = pk2(p1[8 * k2 + 4], p1[8 * k2 + 5]); w.w = pk2(p1[8 * k2 + 6], p1[8 * k2 + 7]); }
;                 pb[ks] = __builtin_bit_cast(bf16x8, w); }
; #pragma unroll
;             for (int db = 0; db < NDB; ++db)
; #pragma unroll
;                 for (int ks = 0; ks < 4; ++ks) {
;                     const bf16x8 vf = *(const bf16x8*)(Vt + (dp * DVW + db * 32 + r32) * VP + ks * 16 + hi * 8);
;                     o[db] = __builtin_amdgcn_mfma_f32_32x32x16_bf16(vf, pb[ks], o[db], 0, 0, 0);
;                 }
	v_mfma_f32_32x32x16_bf16 v[32:47], v[230:233], v[200:203], v[32:47]
	ds_read_b128 v[230:233], v206 offset:43040
	ds_read_b128 v[238:241], v206 offset:47616
	v_mul_f32_e64 v18, v18, v80
	v_mul_f32_e64 v19, v19, v80
	v_mul_f32_e64 v16, v16, v80
	v_mul_f32_e64 v17, v17, v80
	v_pk_mul_f32 v[14:15], v[14:15], v[80:81] op_sel_hi:[1,0]
	v_pk_mul_f32 v[12:13], v[12:13], v[80:81] op_sel_hi:[1,0]
	v_pk_mul_f32 v[10:11], v[10:11], v[80:81] op_sel_hi:[1,0]
	v_pk_mul_f32 v[8:9], v[8:9], v[80:81] op_sel_hi:[1,0]
	s_waitcnt lgkmcnt(2)
	v_mfma_f32_32x32x16_bf16 v[16:31], v[76:79], v[200:203], v[16:31]
	v_mul_f32_e64 v6, v6, v80
	v_mul_f32_e64 v7, v7, v80
	v_mul_f32_e64 v4, v4, v80
	v_mul_f32_e64 v5, v5, v80
	v_mul_f32_e64 v2, v2, v80
	v_mul_f32_e64 v3, v3, v80
	v_pk_mul_f32 v[0:1], v[0:1], v[80:81] op_sel_hi:[1,0]
	ds_read_b128 v[76:79], v206 offset:47648
	v_add_f32_e32 v81, v81, v209
	v_add_f32_e32 v204, v208, v211
	s_waitcnt lgkmcnt(1)
	v_mfma_f32_32x32x16_bf16 v[0:15], v[238:241], v[200:203], v[0:15]
	v_add_f32_e32 v81, 0, v81
	v_add_f32_e32 v205, v210, v213
	v_add_f32_e32 v81, v204, v81
	v_mov_b32_e32 v217, v207
	v_add_f32_e32 v207, v212, v214
	v_add_f32_e32 v81, v205, v81
	v_add_f32_e32 v81, v207, v81
	v_mfma_f32_32x32x16_bf16 v[48:63], v[218:221], v[72:75], v[48:63]
	v_mfma_f32_32x32x16_bf16 v[32:47], v[234:237], v[72:75], v[32:47]
	v_mfma_f32_32x32x16_bf16 v[16:31], v[230:233], v[72:75], v[16:31]
	s_waitcnt lgkmcnt(0)
	v_mfma_f32_32x32x16_bf16 v[0:15], v[76:79], v[72:75], v[0:15]
	ds_read_b128 v[72:75], v206 offset:33856
	ds_read_b128 v[76:79], v206 offset:33888
	s_waitcnt lgkmcnt(1)
	v_mfma_f32_32x32x16_bf16 v[48:63], v[72:75], v[68:71], v[48:63]
	ds_read_b128 v[72:75], v206 offset:38464
	ds_read_b128 v[200:203], v206 offset:38496
	s_waitcnt lgkmcnt(1)
	v_mfma_f32_32x32x16_bf16 v[32:47], v[72:75], v[68:71], v[32:47]
	ds_read_b128 v[72:75], v206 offset:43072
	ds_read_b128 v[218:221], v206 offset:43104
	s_waitcnt lgkmcnt(1)
	v_mfma_f32_32x32x16_bf16 v[16:31], v[72:75], v[68:71], v[16:31]
	ds_read_b128 v[72:75], v206 offset:47680
	ds_read_b128 v[230:233], v206 offset:47712
	s_waitcnt lgkmcnt(1)
	v_mfma_f32_32x32x16_bf16 v[0:15], v[72:75], v[68:71], v[0:15]
	v_add_f32_e64 v68, v82, v84
	v_add_f32_e64 v69, v83, v85
	v_add_f32_e64 v70, v86, v88
	v_add_f32_e64 v71, v87, v89
	v_add_f32_e32 v69, v69, v81
	v_add_f32_e32 v68, v68, v69
	v_add_f32_e32 v68, v71, v68
	v_pk_add_f32 v[72:73], v[90:91], v[92:93]
	v_add_f32_e32 v68, v70, v68
	v_add_f32_e32 v68, v73, v68
	v_mfma_f32_32x32x16_bf16 v[48:63], v[76:79], v[64:67], v[48:63]
	v_add_f32_e64 v74, v94, v180
	v_add_f32_e64 v75, v95, v181
	v_add_f32_e32 v68, v72, v68
	v_add_f32_e64 v76, v182, v184
	v_add_f32_e64 v77, v183, v185
	v_pk_add_f32 v[78:79], v[186:187], v[188:189]
	v_mfma_f32_32x32x16_bf16 v[32:47], v[200:203], v[64:67], v[32:47]
	v_mfma_f32_32x32x16_bf16 v[16:31], v[218:221], v[64:67], v[16:31]
	s_waitcnt lgkmcnt(0)
	v_mfma_f32_32x32x16_bf16 v[0:15], v[230:233], v[64:67], v[0:15]
	v_add_f32_e32 v64, v75, v68
	v_add_f32_e32 v64, v74, v64
	v_add_f32_e32 v64, v77, v64
	v_add_f32_e32 v64, v76, v64
	v_add_f32_e32 v64, v79, v64
	v_add_f32_e32 v216, v78, v64
	v_fmac_f32_e32 v216, v215, v80
	s_cbranch_scc1 .LBB0_1709
; DEV void st4(bf16_t* p, f32x4 v) { u32x2 w; w.x = pk2(v[0], v[1]); w.y = pk2(v[2], v[3]); *(u32x2*)p = w; }
; template <int DQK, int DV, int NDP, int MODE, bool PF>
; DEV void attn_unit(unsigned char* lds, const bf16_t* Q, int ldq, const bf16_t* K, int ldk, const bf16_t* VT, int ldvt, bf16_t* O, int ldo,
;                    int kt0, int ntiles, int qpos0, const float* biasg, float sinkl2) {
;     ...
;     const float ltot = lrun + __shfl_xor(lrun, 32), inv = 1.f / ltot;
;     bf16_t* orow = O + (size_t)(qg * 32 + r32) * ldo + dp * DVW;
; #pragma unroll
;     for (int db = 0; db < NDB; ++db)
; #pragma unroll
;         for (int g4 = 0; g4 < 4; ++g4) { f32x4 w = {o[db][4 * g4] * inv, o[db][4 * g4 + 1] * inv, o[db][4 * g4 + 2] * inv, o[db][4 * g4 + 3] * inv}; st4(orow + db * 32 + 8 * g4 + 4 * hi, w); }
	ds_bpermute_b32 v64, v190, v216
	s_lshl_b64 s[6:7], s[6:7], 1
	s_add_u32 s12, s16, s6
	s_addc_u32 s13, s17, s7
	s_waitcnt lgkmcnt(0)
	v_add_f32_e32 v64, v216, v64
	v_div_scale_f32 v65, s[6:7], v64, v64, 1.0
	v_rcp_f32_e32 v66, v65
	s_lshl_b32 s6, s11, 1
	s_add_u32 s6, s12, s6
	s_addc_u32 s7, s13, 0
	v_fma_f32 v67, -v65, v66, 1.0
	v_fmac_f32_e32 v66, v67, v66
	v_div_scale_f32 v67, vcc, 1.0, v64, 1.0
	v_mul_f32_e32 v68, v67, v66
	v_fma_f32 v69, -v65, v68, v67
	v_fmac_f32_e32 v68, v69, v66
	v_fma_f32 v65, -v65, v68, v67
	v_div_fmas_f32 v65, v65, v66, v68
	v_div_fixup_f32 v68, v65, v64, 1.0
	v_lshl_add_u64 v[64:65], s[6:7], 0, v[162:163]
	s_ashr_i32 s11, s10, 31
	v_lshl_add_u64 v[64:65], s[10:11], 1, v[64:65]
	v_lshlrev_b32_e32 v66, 3, v129
	v_mov_b32_e32 v67, v128
	v_lshl_add_u64 v[64:65], v[64:65], 0, v[66:67]
	v_lshl_add_u64 v[64:65], v[64:65], 0, v[66:67]
	v_mul_f32_e32 v48, v48, v68
	v_mul_f32_e32 v49, v49, v68
	v_mul_f32_e32 v50, v50, v68
	v_mul_f32_e32 v51, v51, v68
	v_mul_f32_e32 v52, v52, v68
	v_mul_f32_e32 v53, v53, v68
	v_mul_f32_e32 v54, v54, v68
	v_mul_f32_e32 v55, v55, v68
	v_cvt_pk_bf16_f32 v48, v48, v49
	v_cvt_pk_bf16_f32 v49, v50, v51
	v_cvt_pk_bf16_f32 v50, v52, v53
	v_cvt_pk_bf16_f32 v51, v54, v55
	s_nop 1
	v_permlane32_swap_b32_e32 v48, v50
	v_permlane32_swap_b32_e32 v49, v51
	flat_store_dwordx4 v[64:65], v[48:51]
	v_mul_f32_e32 v56, v56, v68
	v_mul_f32_e32 v57, v57, v68
	v_mul_f32_e32 v58, v58, v68
	v_mul_f32_e32 v59, v59, v68
	v_mul_f32_e32 v60, v60, v68
	v_mul_f32_e32 v61, v61, v68
	v_mul_f32_e32 v62, v62, v68
	v_mul_f32_e32 v63, v63, v68
	v_cvt_pk_bf16_f32 v56, v56, v57
	v_cvt_pk_bf16_f32 v57, v58, v59
	v_cvt_pk_bf16_f32 v58, v60, v61
	v_cvt_pk_bf16_f32 v59, v62, v63
	s_nop 1
	v_permlane32_swap_b32_e32 v56, v58
	v_permlane32_swap_b32_e32 v57, v59
	flat_store_dwordx4 v[64:65], v[56:59] offset:32
	v_mul_f32_e32 v32, v32, v68
	v_mul_f32_e32 v33, v33, v68
	v_mul_f32_e32 v34, v34, v68
	v_mul_f32_e32 v35, v35, v68
	v_mul_f32_e32 v36, v36, v68
	v_mul_f32_e32 v37, v37, v68
	v_mul_f32_e32 v38, v38, v68
	v_mul_f32_e32 v39, v39, v68
	v_cvt_pk_bf16_f32 v32, v32, v33
	v_cvt_pk_bf16_f32 v33, v34, v35
	v_cvt_pk_bf16_f32 v34, v36, v37
	v_cvt_pk_bf16_f32 v35, v38, v39
	s_nop 1
	v_permlane32_swap_b32_e32 v32, v34
	v_permlane32_swap_b32_e32 v33, v35
	flat_store_dwordx4 v[64:65], v[32:35] offset:64
	v_mul_f32_e32 v40, v40, v68
	v_mul_f32_e32 v41, v41, v68
	v_mul_f32_e32 v42, v42, v68
	v_mul_f32_e32 v43, v43, v68
	v_mul_f32_e32 v44, v44, v68
	v_mul_f32_e32 v45, v45, v68
	v_mul_f32_e32 v46, v46, v68
	v_mul_f32_e32 v47, v47, v68
	v_cvt_pk_bf16_f32 v40, v40, v41
	v_cvt_pk_bf16_f32 v41, v42, v43
	v_cvt_pk_bf16_f32 v42, v44, v45
	v_cvt_pk_bf16_f32 v43, v46, v47
	s_nop 1
	v_permlane32_swap_b32_e32 v40, v42
	v_permlane32_swap_b32_e32 v41, v43
	flat_store_dwordx4 v[64:65], v[40:43] offset:96
	v_mul_f32_e32 v16, v16, v68
	v_mul_f32_e32 v17, v17, v68
	v_mul_f32_e32 v18, v18, v68
	v_mul_f32_e32 v19, v19, v68
	v_mul_f32_e32 v20, v20, v68
	v_mul_f32_e32 v21, v21, v68
	v_mul_f32_e32 v22, v22, v68
	v_mul_f32_e32 v23, v23, v68
	v_cvt_pk_bf16_f32 v16, v16, v17
	v_cvt_pk_bf16_f32 v17, v18, v19
	v_cvt_pk_bf16_f32 v18, v20, v21
	v_cvt_pk_bf16_f32 v19, v22, v23
	s_nop 1
	v_permlane32_swap_b32_e32 v16, v18
	v_permlane32_swap_b32_e32 v17, v19
	flat_store_dwordx4 v[64:65], v[16:19] offset:128
	v_mul_f32_e32 v24, v24, v68
	v_mul_f32_e32 v25, v25, v68
	v_mul_f32_e32 v26, v26, v68
	v_mul_f32_e32 v27, v27, v68
	v_mul_f32_e32 v28, v28, v68
	v_mul_f32_e32 v29, v29, v68
	v_mul_f32_e32 v30, v30, v68
	v_mul_f32_e32 v31, v31, v68
	v_cvt_pk_bf16_f32 v24, v24, v25
	v_cvt_pk_bf16_f32 v25, v26, v27
	v_cvt_pk_bf16_f32 v26, v28, v29
	v_cvt_pk_bf16_f32 v27, v30, v31
	s_nop 1
	v_permlane32_swap_b32_e32 v24, v26
	v_permlane32_swap_b32_e32 v25, v27
	flat_store_dwordx4 v[64:65], v[24:27] offset:160
	v_mul_f32_e32 v0, v0, v68
	v_mul_f32_e32 v1, v1, v68
	v_mul_f32_e32 v2, v2, v68
	v_mul_f32_e32 v3, v3, v68
	v_mul_f32_e32 v4, v4, v68
	v_mul_f32_e32 v5, v5, v68
	v_mul_f32_e32 v6, v6, v68
	v_mul_f32_e32 v7, v7, v68
	v_cvt_pk_bf16_f32 v0, v0, v1
	v_cvt_pk_bf16_f32 v1, v2, v3
	v_cvt_pk_bf16_f32 v2, v4, v5
	v_cvt_pk_bf16_f32 v3, v6, v7
	s_nop 1
	v_permlane32_swap_b32_e32 v0, v2
	v_permlane32_swap_b32_e32 v1, v3
	flat_store_dwordx4 v[64:65], v[0:3] offset:192
	v_mul_f32_e32 v8, v8, v68
	v_mul_f32_e32 v9, v9, v68
	v_mul_f32_e32 v10, v10, v68
	v_mul_f32_e32 v11, v11, v68
	v_mul_f32_e32 v12, v12, v68
	v_mul_f32_e32 v13, v13, v68
	v_mul_f32_e32 v14, v14, v68
	v_mul_f32_e32 v15, v15, v68
	v_cvt_pk_bf16_f32 v8, v8, v9
	v_cvt_pk_bf16_f32 v9, v10, v11
	v_cvt_pk_bf16_f32 v10, v12, v13
	v_cvt_pk_bf16_f32 v11, v14, v15
	s_nop 1
	v_permlane32_swap_b32_e32 v8, v10
	v_permlane32_swap_b32_e32 v9, v11
	flat_store_dwordx4 v[64:65], v[8:11] offset:224
	v_readlane_b32 s6, v254, 0
	s_nop 1
	s_add_i32 s19, s19, s6
	v_readlane_b32 s6, v255, 22
	s_nop 1
	s_add_i32 s18, s18, s6
	s_cmpk_gt_i32 s19, 0x3ff
	v_readlane_b32 s7, v254, 1
	s_cbranch_scc0 .LBB0_1708
